# K-loops (P1,S4,S5): LDS-DMA loads use SGPR base + VGPR offset, 16 address VALU per body removed; S4 cache-copy stores moved to epilogue end
# speedup vs baseline: 1.0022x; 1.0019x over previous
.LBB0_368:
	ds_read_b128 v[114:117], v197
	ds_read_b128 v[134:137], v197 offset:1024
	ds_read_b128 v[138:141], v197 offset:2048
	ds_read_b128 v[142:145], v197 offset:3072
	ds_read_b128 v[146:149], v198
	ds_read_b128 v[150:153], v198 offset:1024
	ds_read_b128 v[154:157], v198 offset:2048
	ds_read_b128 v[158:161], v198 offset:3072
	s_add_u32 s0, s6, 0xfffc0080
	s_addc_u32 s8, s7, -1
	s_cmp_eq_u32 s26, 12
	s_cselect_b32 s11, s2, s8
	s_cselect_b32 s10, s3, s0
	s_cselect_b32 s9, s12, s25
	s_cselect_b32 s8, s13, s24
	s_add_i32 m0, s31, 0xc000
	ds_read_b128 v[184:187], v199
	ds_read_b128 v[188:191], v199 offset:1024
	ds_read_b128 v[206:209], v199 offset:2048
	ds_read_b128 v[210:213], v199 offset:3072
	ds_read_b128 v[214:217], v199 offset:4096
	ds_read_b128 v[218:221], v199 offset:5120
	ds_read_b128 v[222:225], v199 offset:6144
	ds_read_b128 v[226:229], v199 offset:7168
	global_load_lds_dwordx4 v180, s[6:7]
	s_add_i32 m0, s31, 0xe000
	s_nop 0
	global_load_lds_dwordx4 v182, s[6:7]
	s_waitcnt vmcnt(8)
	s_waitcnt lgkmcnt(0)
	s_barrier
	s_setprio 1
	s_waitcnt lgkmcnt(0)
	v_mfma_f32_16x16x32_bf16 v[130:133], v[114:117], v[184:187], v[130:133]
	v_mfma_f32_16x16x32_bf16 v[126:129], v[138:141], v[184:187], v[126:129]
	v_mfma_f32_16x16x32_bf16 v[110:113], v[114:117], v[206:209], v[110:113]
	v_mfma_f32_16x16x32_bf16 v[106:109], v[138:141], v[206:209], v[106:109]
	v_mfma_f32_16x16x32_bf16 v[94:97], v[114:117], v[214:217], v[94:97]
	v_mfma_f32_16x16x32_bf16 v[90:93], v[138:141], v[214:217], v[90:93]
	v_mfma_f32_16x16x32_bf16 v[78:81], v[114:117], v[222:225], v[78:81]
	v_mfma_f32_16x16x32_bf16 v[74:77], v[138:141], v[222:225], v[74:77]
	v_mfma_f32_16x16x32_bf16 v[130:133], v[134:137], v[188:191], v[130:133]
	v_mfma_f32_16x16x32_bf16 v[126:129], v[142:145], v[188:191], v[126:129]
	v_mfma_f32_16x16x32_bf16 v[110:113], v[134:137], v[210:213], v[110:113]
	v_mfma_f32_16x16x32_bf16 v[106:109], v[142:145], v[210:213], v[106:109]
	v_mfma_f32_16x16x32_bf16 v[94:97], v[134:137], v[218:221], v[94:97]
	v_mfma_f32_16x16x32_bf16 v[90:93], v[142:145], v[218:221], v[90:93]
	v_mfma_f32_16x16x32_bf16 v[78:81], v[134:137], v[226:229], v[78:81]
	v_mfma_f32_16x16x32_bf16 v[74:77], v[142:145], v[226:229], v[74:77]
	s_setprio 0
	s_setprio 1
	v_mfma_f32_16x16x32_bf16 v[122:125], v[146:149], v[184:187], v[122:125]
	v_mfma_f32_16x16x32_bf16 v[118:121], v[154:157], v[184:187], v[118:121]
	v_mfma_f32_16x16x32_bf16 v[102:105], v[146:149], v[206:209], v[102:105]
	v_mfma_f32_16x16x32_bf16 v[98:101], v[154:157], v[206:209], v[98:101]
	v_mfma_f32_16x16x32_bf16 v[86:89], v[146:149], v[214:217], v[86:89]
	v_mfma_f32_16x16x32_bf16 v[82:85], v[154:157], v[214:217], v[82:85]
	v_mfma_f32_16x16x32_bf16 v[70:73], v[146:149], v[222:225], v[70:73]
	v_mfma_f32_16x16x32_bf16 v[66:69], v[154:157], v[222:225], v[66:69]
	v_mfma_f32_16x16x32_bf16 v[122:125], v[150:153], v[188:191], v[122:125]
	v_mfma_f32_16x16x32_bf16 v[118:121], v[158:161], v[188:191], v[118:121]
	v_mfma_f32_16x16x32_bf16 v[102:105], v[150:153], v[210:213], v[102:105]
	v_mfma_f32_16x16x32_bf16 v[98:101], v[158:161], v[210:213], v[98:101]
	v_mfma_f32_16x16x32_bf16 v[86:89], v[150:153], v[218:221], v[86:89]
	v_mfma_f32_16x16x32_bf16 v[82:85], v[158:161], v[218:221], v[82:85]
	v_mfma_f32_16x16x32_bf16 v[70:73], v[150:153], v[226:229], v[70:73]
	v_mfma_f32_16x16x32_bf16 v[66:69], v[158:161], v[226:229], v[66:69]
	s_setprio 0
	s_barrier
	s_add_i32 s0, s89, s79
	s_mov_b32 m0, s0
	ds_read_b128 v[184:187], v199 offset:16384
	ds_read_b128 v[188:191], v199 offset:17408
	ds_read_b128 v[206:209], v199 offset:18432
	ds_read_b128 v[210:213], v199 offset:19456
	ds_read_b128 v[214:217], v199 offset:20480
	ds_read_b128 v[218:221], v199 offset:21504
	ds_read_b128 v[222:225], v199 offset:22528
	ds_read_b128 v[226:229], v199 offset:23552
	global_load_lds_dwordx4 v164, s[8:9]
	s_add_i32 m0, s0, 0x2000
	s_add_u32 s62, s8, 0x40000
	s_addc_u32 s63, s9, 0
	s_add_i32 s0, s90, s79
	global_load_lds_dwordx4 v168, s[8:9]
	s_mov_b32 m0, s0
	s_nop 0
	global_load_lds_dwordx4 v164, s[62:63]
	s_add_i32 m0, s0, 0x2000
	s_nop 0
	global_load_lds_dwordx4 v168, s[62:63]
	s_mov_b32 m0, s31
	s_nop 0
	global_load_lds_dwordx4 v162, s[10:11]
	s_mov_b32 m0, s80
	s_nop 0
	global_load_lds_dwordx4 v166, s[10:11]
	s_waitcnt vmcnt(8)
	s_waitcnt lgkmcnt(0)
	s_barrier
	s_setprio 1
	s_waitcnt lgkmcnt(0)
	v_mfma_f32_16x16x32_bf16 v[62:65], v[114:117], v[184:187], v[62:65]
	v_mfma_f32_16x16x32_bf16 v[58:61], v[138:141], v[184:187], v[58:61]
	v_mfma_f32_16x16x32_bf16 v[46:49], v[114:117], v[206:209], v[46:49]
	v_mfma_f32_16x16x32_bf16 v[42:45], v[138:141], v[206:209], v[42:45]
	v_mfma_f32_16x16x32_bf16 v[30:33], v[114:117], v[214:217], v[30:33]
	v_mfma_f32_16x16x32_bf16 v[26:29], v[138:141], v[214:217], v[26:29]
	v_mfma_f32_16x16x32_bf16 v[14:17], v[114:117], v[222:225], v[14:17]
	v_mfma_f32_16x16x32_bf16 v[10:13], v[138:141], v[222:225], v[10:13]
	v_mfma_f32_16x16x32_bf16 v[62:65], v[134:137], v[188:191], v[62:65]
	v_mfma_f32_16x16x32_bf16 v[58:61], v[142:145], v[188:191], v[58:61]
	v_mfma_f32_16x16x32_bf16 v[46:49], v[134:137], v[210:213], v[46:49]
	v_mfma_f32_16x16x32_bf16 v[42:45], v[142:145], v[210:213], v[42:45]
	v_mfma_f32_16x16x32_bf16 v[30:33], v[134:137], v[218:221], v[30:33]
	v_mfma_f32_16x16x32_bf16 v[26:29], v[142:145], v[218:221], v[26:29]
	v_mfma_f32_16x16x32_bf16 v[14:17], v[134:137], v[226:229], v[14:17]
	v_mfma_f32_16x16x32_bf16 v[10:13], v[142:145], v[226:229], v[10:13]
	s_setprio 0
	s_setprio 1
	v_mfma_f32_16x16x32_bf16 v[54:57], v[146:149], v[184:187], v[54:57]
	v_mfma_f32_16x16x32_bf16 v[50:53], v[154:157], v[184:187], v[50:53]
	v_mfma_f32_16x16x32_bf16 v[38:41], v[146:149], v[206:209], v[38:41]
	v_mfma_f32_16x16x32_bf16 v[34:37], v[154:157], v[206:209], v[34:37]
	v_mfma_f32_16x16x32_bf16 v[22:25], v[146:149], v[214:217], v[22:25]
	v_mfma_f32_16x16x32_bf16 v[18:21], v[154:157], v[214:217], v[18:21]
	v_mfma_f32_16x16x32_bf16 v[6:9], v[146:149], v[222:225], v[6:9]
	v_mfma_f32_16x16x32_bf16 v[2:5], v[154:157], v[222:225], v[2:5]
	v_mfma_f32_16x16x32_bf16 v[54:57], v[150:153], v[188:191], v[54:57]
	v_mfma_f32_16x16x32_bf16 v[50:53], v[158:161], v[188:191], v[50:53]
	v_mfma_f32_16x16x32_bf16 v[38:41], v[150:153], v[210:213], v[38:41]
	v_mfma_f32_16x16x32_bf16 v[34:37], v[158:161], v[210:213], v[34:37]
	v_mfma_f32_16x16x32_bf16 v[22:25], v[150:153], v[218:221], v[22:25]
	v_mfma_f32_16x16x32_bf16 v[18:21], v[158:161], v[218:221], v[18:21]
	v_mfma_f32_16x16x32_bf16 v[6:9], v[150:153], v[226:229], v[6:9]
	v_mfma_f32_16x16x32_bf16 v[2:5], v[158:161], v[226:229], v[2:5]
	s_setprio 0
	s_barrier
	s_add_i32 s0, 0, 0x18000
	s_add_i32 s27, 0, 0x1c000
	v_add_u32_e32 v142, s0, v173
	v_add_u32_e32 v158, s27, v173
	ds_read_b128 v[114:117], v142
	ds_read_b128 v[134:137], v142 offset:1024
	ds_read_b128 v[138:141], v142 offset:2048
	ds_read_b128 v[142:145], v142 offset:3072
	ds_read_b128 v[146:149], v158
	ds_read_b128 v[150:153], v158 offset:1024
	ds_read_b128 v[154:157], v158 offset:2048
	ds_read_b128 v[158:161], v158 offset:3072
	s_add_u32 s10, s10, 0x40000
	s_addc_u32 s11, s11, 0
	s_mov_b32 m0, s81
	ds_read_b128 v[184:187], v199 offset:32768
	ds_read_b128 v[188:191], v199 offset:33792
	ds_read_b128 v[206:209], v199 offset:34816
	ds_read_b128 v[210:213], v199 offset:35840
	ds_read_b128 v[214:217], v199 offset:36864
	ds_read_b128 v[218:221], v199 offset:37888
	ds_read_b128 v[222:225], v199 offset:38912
	ds_read_b128 v[226:229], v199 offset:39936
	global_load_lds_dwordx4 v162, s[10:11]
	s_mov_b32 m0, s82
	s_nop 0
	global_load_lds_dwordx4 v166, s[10:11]
	s_waitcnt vmcnt(8)
	s_waitcnt lgkmcnt(0)
	s_barrier
	s_setprio 1
	s_waitcnt lgkmcnt(0)
	v_mfma_f32_16x16x32_bf16 v[130:133], v[114:117], v[184:187], v[130:133]
	v_mfma_f32_16x16x32_bf16 v[126:129], v[138:141], v[184:187], v[126:129]
	v_mfma_f32_16x16x32_bf16 v[110:113], v[114:117], v[206:209], v[110:113]
	v_mfma_f32_16x16x32_bf16 v[106:109], v[138:141], v[206:209], v[106:109]
	v_mfma_f32_16x16x32_bf16 v[94:97], v[114:117], v[214:217], v[94:97]
	v_mfma_f32_16x16x32_bf16 v[90:93], v[138:141], v[214:217], v[90:93]
	v_mfma_f32_16x16x32_bf16 v[78:81], v[114:117], v[222:225], v[78:81]
	v_mfma_f32_16x16x32_bf16 v[74:77], v[138:141], v[222:225], v[74:77]
	v_mfma_f32_16x16x32_bf16 v[130:133], v[134:137], v[188:191], v[130:133]
	v_mfma_f32_16x16x32_bf16 v[126:129], v[142:145], v[188:191], v[126:129]
	v_mfma_f32_16x16x32_bf16 v[110:113], v[134:137], v[210:213], v[110:113]
	v_mfma_f32_16x16x32_bf16 v[106:109], v[142:145], v[210:213], v[106:109]
	v_mfma_f32_16x16x32_bf16 v[94:97], v[134:137], v[218:221], v[94:97]
	v_mfma_f32_16x16x32_bf16 v[90:93], v[142:145], v[218:221], v[90:93]
	v_mfma_f32_16x16x32_bf16 v[78:81], v[134:137], v[226:229], v[78:81]
	v_mfma_f32_16x16x32_bf16 v[74:77], v[142:145], v[226:229], v[74:77]
	s_setprio 0
	s_setprio 1
	v_mfma_f32_16x16x32_bf16 v[122:125], v[146:149], v[184:187], v[122:125]
	v_mfma_f32_16x16x32_bf16 v[118:121], v[154:157], v[184:187], v[118:121]
	v_mfma_f32_16x16x32_bf16 v[102:105], v[146:149], v[206:209], v[102:105]
	v_mfma_f32_16x16x32_bf16 v[98:101], v[154:157], v[206:209], v[98:101]
	v_mfma_f32_16x16x32_bf16 v[86:89], v[146:149], v[214:217], v[86:89]
	v_mfma_f32_16x16x32_bf16 v[82:85], v[154:157], v[214:217], v[82:85]
	v_mfma_f32_16x16x32_bf16 v[70:73], v[146:149], v[222:225], v[70:73]
	v_mfma_f32_16x16x32_bf16 v[66:69], v[154:157], v[222:225], v[66:69]
	v_mfma_f32_16x16x32_bf16 v[122:125], v[150:153], v[188:191], v[122:125]
	v_mfma_f32_16x16x32_bf16 v[118:121], v[158:161], v[188:191], v[118:121]
	v_mfma_f32_16x16x32_bf16 v[102:105], v[150:153], v[210:213], v[102:105]
	v_mfma_f32_16x16x32_bf16 v[98:101], v[158:161], v[210:213], v[98:101]
	v_mfma_f32_16x16x32_bf16 v[86:89], v[150:153], v[218:221], v[86:89]
	v_mfma_f32_16x16x32_bf16 v[82:85], v[158:161], v[218:221], v[82:85]
	v_mfma_f32_16x16x32_bf16 v[70:73], v[150:153], v[226:229], v[70:73]
	v_mfma_f32_16x16x32_bf16 v[66:69], v[158:161], v[226:229], v[66:69]
	s_setprio 0
	s_barrier
	s_add_i32 s0, s0, s79
	s_mov_b32 m0, s0
	ds_read_b128 v[184:187], v199 offset:49152
	ds_read_b128 v[188:191], v199 offset:50176
	ds_read_b128 v[206:209], v199 offset:51200
	ds_read_b128 v[210:213], v199 offset:52224
	ds_read_b128 v[214:217], v199 offset:53248
	ds_read_b128 v[218:221], v199 offset:54272
	ds_read_b128 v[222:225], v199 offset:55296
	ds_read_b128 v[226:229], v199 offset:56320
	s_add_u32 s98, s8, 0x80
	s_addc_u32 s99, s9, 0
	global_load_lds_dwordx4 v164, s[98:99]
	s_add_i32 m0, s0, 0x2000
	s_add_u32 s8, s8, 0x40080
	s_addc_u32 s9, s9, 0
	s_add_i32 s0, s27, s79
	global_load_lds_dwordx4 v168, s[98:99]
	s_mov_b32 m0, s0
	s_nop 0
	global_load_lds_dwordx4 v164, s[8:9]
	s_add_i32 m0, s0, 0x2000
	s_nop 0
	global_load_lds_dwordx4 v168, s[8:9]
	s_add_u32 s98, s10, 0xfffc0080
	s_addc_u32 s99, s11, -1
	s_mov_b32 m0, s84
	s_nop 0
	global_load_lds_dwordx4 v162, s[98:99]
	s_mov_b32 m0, s85
	s_nop 0
	global_load_lds_dwordx4 v166, s[98:99]
	s_waitcnt vmcnt(8)
	s_waitcnt lgkmcnt(0)
	s_barrier
	s_setprio 1
	s_waitcnt lgkmcnt(0)
	v_mfma_f32_16x16x32_bf16 v[62:65], v[114:117], v[184:187], v[62:65]
	v_mfma_f32_16x16x32_bf16 v[58:61], v[138:141], v[184:187], v[58:61]
	v_mfma_f32_16x16x32_bf16 v[46:49], v[114:117], v[206:209], v[46:49]
	v_mfma_f32_16x16x32_bf16 v[42:45], v[138:141], v[206:209], v[42:45]
	v_mfma_f32_16x16x32_bf16 v[30:33], v[114:117], v[214:217], v[30:33]
	v_mfma_f32_16x16x32_bf16 v[26:29], v[138:141], v[214:217], v[26:29]
	v_mfma_f32_16x16x32_bf16 v[14:17], v[114:117], v[222:225], v[14:17]
	v_mfma_f32_16x16x32_bf16 v[10:13], v[138:141], v[222:225], v[10:13]
	v_mfma_f32_16x16x32_bf16 v[62:65], v[134:137], v[188:191], v[62:65]
	v_mfma_f32_16x16x32_bf16 v[58:61], v[142:145], v[188:191], v[58:61]
	v_mfma_f32_16x16x32_bf16 v[46:49], v[134:137], v[210:213], v[46:49]
	v_mfma_f32_16x16x32_bf16 v[42:45], v[142:145], v[210:213], v[42:45]
	v_mfma_f32_16x16x32_bf16 v[30:33], v[134:137], v[218:221], v[30:33]
	v_mfma_f32_16x16x32_bf16 v[26:29], v[142:145], v[218:221], v[26:29]
	v_mfma_f32_16x16x32_bf16 v[14:17], v[134:137], v[226:229], v[14:17]
	v_mfma_f32_16x16x32_bf16 v[10:13], v[142:145], v[226:229], v[10:13]
	s_setprio 0
	s_setprio 1
	v_mfma_f32_16x16x32_bf16 v[54:57], v[146:149], v[184:187], v[54:57]
	v_mfma_f32_16x16x32_bf16 v[50:53], v[154:157], v[184:187], v[50:53]
	v_mfma_f32_16x16x32_bf16 v[38:41], v[146:149], v[206:209], v[38:41]
	v_mfma_f32_16x16x32_bf16 v[34:37], v[154:157], v[206:209], v[34:37]
	v_mfma_f32_16x16x32_bf16 v[22:25], v[146:149], v[214:217], v[22:25]
	v_mfma_f32_16x16x32_bf16 v[18:21], v[154:157], v[214:217], v[18:21]
	v_mfma_f32_16x16x32_bf16 v[6:9], v[146:149], v[222:225], v[6:9]
	v_mfma_f32_16x16x32_bf16 v[2:5], v[154:157], v[222:225], v[2:5]
	v_mfma_f32_16x16x32_bf16 v[54:57], v[150:153], v[188:191], v[54:57]
	v_mfma_f32_16x16x32_bf16 v[50:53], v[158:161], v[188:191], v[50:53]
	v_mfma_f32_16x16x32_bf16 v[38:41], v[150:153], v[210:213], v[38:41]
	v_mfma_f32_16x16x32_bf16 v[34:37], v[158:161], v[210:213], v[34:37]
	v_mfma_f32_16x16x32_bf16 v[22:25], v[150:153], v[218:221], v[22:25]
	v_mfma_f32_16x16x32_bf16 v[18:21], v[158:161], v[218:221], v[18:21]
	v_mfma_f32_16x16x32_bf16 v[6:9], v[150:153], v[226:229], v[6:9]
	v_mfma_f32_16x16x32_bf16 v[2:5], v[158:161], v[226:229], v[2:5]
	s_setprio 0
	s_barrier
	s_add_i32 s26, s26, 2
	s_add_u32 s6, s6, 0x100
	s_addc_u32 s7, s7, 0
	s_add_u32 s24, s24, 0x100
	s_addc_u32 s25, s25, 0
	s_cmp_gt_u32 s26, 13
	s_cbranch_scc0 .LBB0_368
	s_and_b64 vcc, exec, s[46:47]
	s_cbranch_vccz .LBB0_371

.LBB0_991:
	ds_read_b128 v[66:69], v219
	ds_read_b128 v[70:73], v219 offset:1024
	ds_read_b128 v[86:89], v219 offset:2048
	ds_read_b128 v[106:109], v219 offset:3072
	ds_read_b128 v[146:149], v220
	ds_read_b128 v[150:153], v220 offset:1024
	ds_read_b128 v[154:157], v220 offset:2048
	ds_read_b128 v[158:161], v220 offset:3072
	s_add_u32 s10, s8, 0xfffc0080
	s_addc_u32 s11, s9, -1
	s_cmp_eq_u32 s22, 12
	s_cselect_b32 s45, s1, s11
	s_cselect_b32 s44, s2, s10
	s_cselect_b32 s11, s3, s7
	s_cselect_b32 s10, s4, s5
	s_add_i32 m0, s54, 0xc000
	ds_read_b128 v[162:165], v221
	ds_read_b128 v[166:169], v221 offset:1024
	ds_read_b128 v[170:173], v221 offset:2048
	ds_read_b128 v[174:177], v221 offset:3072
	ds_read_b128 v[196:199], v221 offset:4096
	ds_read_b128 v[200:203], v221 offset:5120
	ds_read_b128 v[204:207], v221 offset:6144
	ds_read_b128 v[208:211], v221 offset:7168
	global_load_lds_dwordx4 v192, s[8:9]
	s_add_i32 m0, s54, 0xe000
	s_nop 0
	global_load_lds_dwordx4 v194, s[8:9]
	s_waitcnt vmcnt(8)
	s_waitcnt lgkmcnt(0)
	s_barrier
	s_setprio 1
	s_waitcnt lgkmcnt(0)
	v_mfma_f32_16x16x32_bf16 v[142:145], v[66:69], v[162:165], v[142:145]
	v_mfma_f32_16x16x32_bf16 v[134:137], v[86:89], v[162:165], v[134:137]
	v_mfma_f32_16x16x32_bf16 v[126:129], v[66:69], v[170:173], v[126:129]
	v_mfma_f32_16x16x32_bf16 v[122:125], v[86:89], v[170:173], v[122:125]
	v_mfma_f32_16x16x32_bf16 v[110:113], v[66:69], v[196:199], v[110:113]
	v_mfma_f32_16x16x32_bf16 v[102:105], v[86:89], v[196:199], v[102:105]
	v_mfma_f32_16x16x32_bf16 v[90:93], v[66:69], v[204:207], v[90:93]
	v_mfma_f32_16x16x32_bf16 v[82:85], v[86:89], v[204:207], v[82:85]
	v_mfma_f32_16x16x32_bf16 v[142:145], v[70:73], v[166:169], v[142:145]
	v_mfma_f32_16x16x32_bf16 v[134:137], v[106:109], v[166:169], v[134:137]
	v_mfma_f32_16x16x32_bf16 v[126:129], v[70:73], v[174:177], v[126:129]
	v_mfma_f32_16x16x32_bf16 v[122:125], v[106:109], v[174:177], v[122:125]
	v_mfma_f32_16x16x32_bf16 v[110:113], v[70:73], v[200:203], v[110:113]
	v_mfma_f32_16x16x32_bf16 v[102:105], v[106:109], v[200:203], v[102:105]
	v_mfma_f32_16x16x32_bf16 v[90:93], v[70:73], v[208:211], v[90:93]
	v_mfma_f32_16x16x32_bf16 v[82:85], v[106:109], v[208:211], v[82:85]
	s_setprio 0
	s_setprio 1
	v_mfma_f32_16x16x32_bf16 v[138:141], v[146:149], v[162:165], v[138:141]
	v_mfma_f32_16x16x32_bf16 v[130:133], v[154:157], v[162:165], v[130:133]
	v_mfma_f32_16x16x32_bf16 v[118:121], v[146:149], v[170:173], v[118:121]
	v_mfma_f32_16x16x32_bf16 v[114:117], v[154:157], v[170:173], v[114:117]
	v_mfma_f32_16x16x32_bf16 v[98:101], v[146:149], v[196:199], v[98:101]
	v_mfma_f32_16x16x32_bf16 v[94:97], v[154:157], v[196:199], v[94:97]
	v_mfma_f32_16x16x32_bf16 v[78:81], v[146:149], v[204:207], v[78:81]
	v_mfma_f32_16x16x32_bf16 v[74:77], v[154:157], v[204:207], v[74:77]
	v_mfma_f32_16x16x32_bf16 v[138:141], v[150:153], v[166:169], v[138:141]
	v_mfma_f32_16x16x32_bf16 v[130:133], v[158:161], v[166:169], v[130:133]
	v_mfma_f32_16x16x32_bf16 v[118:121], v[150:153], v[174:177], v[118:121]
	v_mfma_f32_16x16x32_bf16 v[114:117], v[158:161], v[174:177], v[114:117]
	v_mfma_f32_16x16x32_bf16 v[98:101], v[150:153], v[200:203], v[98:101]
	v_mfma_f32_16x16x32_bf16 v[94:97], v[158:161], v[200:203], v[94:97]
	v_mfma_f32_16x16x32_bf16 v[78:81], v[150:153], v[208:211], v[78:81]
	v_mfma_f32_16x16x32_bf16 v[74:77], v[158:161], v[208:211], v[74:77]
	s_setprio 0
	s_barrier
	s_add_i32 s37, s62, s53
	s_mov_b32 m0, s37
	ds_read_b128 v[162:165], v221 offset:16384
	ds_read_b128 v[166:169], v221 offset:17408
	ds_read_b128 v[170:173], v221 offset:18432
	ds_read_b128 v[174:177], v221 offset:19456
	ds_read_b128 v[196:199], v221 offset:20480
	ds_read_b128 v[200:203], v221 offset:21504
	ds_read_b128 v[204:207], v221 offset:22528
	ds_read_b128 v[208:211], v221 offset:23552
	global_load_lds_dwordx4 v184, s[10:11]
	s_add_i32 m0, s37, 0x2000
	s_add_u32 s46, s10, 0x40000
	s_addc_u32 s47, s11, 0
	s_add_i32 s37, s63, s53
	global_load_lds_dwordx4 v188, s[10:11]
	s_mov_b32 m0, s37
	s_nop 0
	global_load_lds_dwordx4 v184, s[46:47]
	s_add_i32 m0, s37, 0x2000
	s_nop 0
	global_load_lds_dwordx4 v188, s[46:47]
	s_mov_b32 m0, s54
	s_nop 0
	global_load_lds_dwordx4 v182, s[44:45]
	s_mov_b32 m0, s55
	s_nop 0
	global_load_lds_dwordx4 v186, s[44:45]
	s_waitcnt vmcnt(8)
	s_waitcnt lgkmcnt(0)
	s_barrier
	s_setprio 1
	s_waitcnt lgkmcnt(0)
	v_mfma_f32_16x16x32_bf16 v[62:65], v[66:69], v[162:165], v[62:65]
	v_mfma_f32_16x16x32_bf16 v[54:57], v[86:89], v[162:165], v[54:57]
	v_mfma_f32_16x16x32_bf16 v[46:49], v[66:69], v[170:173], v[46:49]
	v_mfma_f32_16x16x32_bf16 v[42:45], v[86:89], v[170:173], v[42:45]
	v_mfma_f32_16x16x32_bf16 v[30:33], v[66:69], v[196:199], v[30:33]
	v_mfma_f32_16x16x32_bf16 v[26:29], v[86:89], v[196:199], v[26:29]
	v_mfma_f32_16x16x32_bf16 v[14:17], v[66:69], v[204:207], v[14:17]
	v_mfma_f32_16x16x32_bf16 v[10:13], v[86:89], v[204:207], v[10:13]
	v_mfma_f32_16x16x32_bf16 v[62:65], v[70:73], v[166:169], v[62:65]
	v_mfma_f32_16x16x32_bf16 v[54:57], v[106:109], v[166:169], v[54:57]
	v_mfma_f32_16x16x32_bf16 v[46:49], v[70:73], v[174:177], v[46:49]
	v_mfma_f32_16x16x32_bf16 v[42:45], v[106:109], v[174:177], v[42:45]
	v_mfma_f32_16x16x32_bf16 v[30:33], v[70:73], v[200:203], v[30:33]
	v_mfma_f32_16x16x32_bf16 v[26:29], v[106:109], v[200:203], v[26:29]
	v_mfma_f32_16x16x32_bf16 v[14:17], v[70:73], v[208:211], v[14:17]
	v_mfma_f32_16x16x32_bf16 v[10:13], v[106:109], v[208:211], v[10:13]
	s_setprio 0
	s_setprio 1
	v_mfma_f32_16x16x32_bf16 v[58:61], v[146:149], v[162:165], v[58:61]
	v_mfma_f32_16x16x32_bf16 v[50:53], v[154:157], v[162:165], v[50:53]
	v_mfma_f32_16x16x32_bf16 v[38:41], v[146:149], v[170:173], v[38:41]
	v_mfma_f32_16x16x32_bf16 v[34:37], v[154:157], v[170:173], v[34:37]
	v_mfma_f32_16x16x32_bf16 v[22:25], v[146:149], v[196:199], v[22:25]
	v_mfma_f32_16x16x32_bf16 v[18:21], v[154:157], v[196:199], v[18:21]
	v_mfma_f32_16x16x32_bf16 v[6:9], v[146:149], v[204:207], v[6:9]
	v_mfma_f32_16x16x32_bf16 v[2:5], v[154:157], v[204:207], v[2:5]
	v_mfma_f32_16x16x32_bf16 v[58:61], v[150:153], v[166:169], v[58:61]
	v_mfma_f32_16x16x32_bf16 v[50:53], v[158:161], v[166:169], v[50:53]
	v_mfma_f32_16x16x32_bf16 v[38:41], v[150:153], v[174:177], v[38:41]
	v_mfma_f32_16x16x32_bf16 v[34:37], v[158:161], v[174:177], v[34:37]
	v_mfma_f32_16x16x32_bf16 v[22:25], v[150:153], v[200:203], v[22:25]
	v_mfma_f32_16x16x32_bf16 v[18:21], v[158:161], v[200:203], v[18:21]
	v_mfma_f32_16x16x32_bf16 v[6:9], v[150:153], v[208:211], v[6:9]
	v_mfma_f32_16x16x32_bf16 v[2:5], v[158:161], v[208:211], v[2:5]
	s_setprio 0
	s_barrier
	s_add_i32 s37, 0, 0x18000
	s_add_i32 s39, 0, 0x1c000
	v_add_u32_e32 v106, s37, v213
	v_add_u32_e32 v158, s39, v213
	ds_read_b128 v[66:69], v106
	ds_read_b128 v[70:73], v106 offset:1024
	ds_read_b128 v[86:89], v106 offset:2048
	ds_read_b128 v[106:109], v106 offset:3072
	ds_read_b128 v[146:149], v158
	ds_read_b128 v[150:153], v158 offset:1024
	ds_read_b128 v[154:157], v158 offset:2048
	ds_read_b128 v[158:161], v158 offset:3072
	s_add_u32 s44, s44, 0x40000
	s_addc_u32 s45, s45, 0
	s_mov_b32 m0, s56
	ds_read_b128 v[162:165], v221 offset:32768
	ds_read_b128 v[166:169], v221 offset:33792
	ds_read_b128 v[170:173], v221 offset:34816
	ds_read_b128 v[174:177], v221 offset:35840
	ds_read_b128 v[196:199], v221 offset:36864
	ds_read_b128 v[200:203], v221 offset:37888
	ds_read_b128 v[204:207], v221 offset:38912
	ds_read_b128 v[208:211], v221 offset:39936
	global_load_lds_dwordx4 v182, s[44:45]
	s_mov_b32 m0, s57
	s_nop 0
	global_load_lds_dwordx4 v186, s[44:45]
	s_waitcnt vmcnt(8)
	s_waitcnt lgkmcnt(0)
	s_barrier
	s_setprio 1
	s_waitcnt lgkmcnt(0)
	v_mfma_f32_16x16x32_bf16 v[142:145], v[66:69], v[162:165], v[142:145]
	v_mfma_f32_16x16x32_bf16 v[134:137], v[86:89], v[162:165], v[134:137]
	v_mfma_f32_16x16x32_bf16 v[126:129], v[66:69], v[170:173], v[126:129]
	v_mfma_f32_16x16x32_bf16 v[122:125], v[86:89], v[170:173], v[122:125]
	v_mfma_f32_16x16x32_bf16 v[110:113], v[66:69], v[196:199], v[110:113]
	v_mfma_f32_16x16x32_bf16 v[102:105], v[86:89], v[196:199], v[102:105]
	v_mfma_f32_16x16x32_bf16 v[90:93], v[66:69], v[204:207], v[90:93]
	v_mfma_f32_16x16x32_bf16 v[82:85], v[86:89], v[204:207], v[82:85]
	v_mfma_f32_16x16x32_bf16 v[142:145], v[70:73], v[166:169], v[142:145]
	v_mfma_f32_16x16x32_bf16 v[134:137], v[106:109], v[166:169], v[134:137]
	v_mfma_f32_16x16x32_bf16 v[126:129], v[70:73], v[174:177], v[126:129]
	v_mfma_f32_16x16x32_bf16 v[122:125], v[106:109], v[174:177], v[122:125]
	v_mfma_f32_16x16x32_bf16 v[110:113], v[70:73], v[200:203], v[110:113]
	v_mfma_f32_16x16x32_bf16 v[102:105], v[106:109], v[200:203], v[102:105]
	v_mfma_f32_16x16x32_bf16 v[90:93], v[70:73], v[208:211], v[90:93]
	v_mfma_f32_16x16x32_bf16 v[82:85], v[106:109], v[208:211], v[82:85]
	s_setprio 0
	s_setprio 1
	v_mfma_f32_16x16x32_bf16 v[138:141], v[146:149], v[162:165], v[138:141]
	v_mfma_f32_16x16x32_bf16 v[130:133], v[154:157], v[162:165], v[130:133]
	v_mfma_f32_16x16x32_bf16 v[118:121], v[146:149], v[170:173], v[118:121]
	v_mfma_f32_16x16x32_bf16 v[114:117], v[154:157], v[170:173], v[114:117]
	v_mfma_f32_16x16x32_bf16 v[98:101], v[146:149], v[196:199], v[98:101]
	v_mfma_f32_16x16x32_bf16 v[94:97], v[154:157], v[196:199], v[94:97]
	v_mfma_f32_16x16x32_bf16 v[78:81], v[146:149], v[204:207], v[78:81]
	v_mfma_f32_16x16x32_bf16 v[74:77], v[154:157], v[204:207], v[74:77]
	v_mfma_f32_16x16x32_bf16 v[138:141], v[150:153], v[166:169], v[138:141]
	v_mfma_f32_16x16x32_bf16 v[130:133], v[158:161], v[166:169], v[130:133]
	v_mfma_f32_16x16x32_bf16 v[118:121], v[150:153], v[174:177], v[118:121]
	v_mfma_f32_16x16x32_bf16 v[114:117], v[158:161], v[174:177], v[114:117]
	v_mfma_f32_16x16x32_bf16 v[98:101], v[150:153], v[200:203], v[98:101]
	v_mfma_f32_16x16x32_bf16 v[94:97], v[158:161], v[200:203], v[94:97]
	v_mfma_f32_16x16x32_bf16 v[78:81], v[150:153], v[208:211], v[78:81]
	v_mfma_f32_16x16x32_bf16 v[74:77], v[158:161], v[208:211], v[74:77]
	s_setprio 0
	s_barrier
	s_add_i32 s37, s37, s53
	s_mov_b32 m0, s37
	ds_read_b128 v[162:165], v221 offset:49152
	ds_read_b128 v[166:169], v221 offset:50176
	ds_read_b128 v[170:173], v221 offset:51200
	ds_read_b128 v[174:177], v221 offset:52224
	ds_read_b128 v[196:199], v221 offset:53248
	ds_read_b128 v[200:203], v221 offset:54272
	ds_read_b128 v[204:207], v221 offset:55296
	ds_read_b128 v[208:211], v221 offset:56320
	s_add_u32 s98, s10, 0x80
	s_addc_u32 s99, s11, 0
	global_load_lds_dwordx4 v184, s[98:99]
	s_add_i32 m0, s37, 0x2000
	s_add_u32 s10, s10, 0x40080
	s_addc_u32 s11, s11, 0
	s_add_i32 s37, s39, s53
	global_load_lds_dwordx4 v188, s[98:99]
	s_mov_b32 m0, s37
	s_nop 0
	global_load_lds_dwordx4 v184, s[10:11]
	s_add_i32 m0, s37, 0x2000
	s_nop 0
	global_load_lds_dwordx4 v188, s[10:11]
	s_add_u32 s98, s44, 0xfffc0080
	s_addc_u32 s99, s45, -1
	s_mov_b32 m0, s60
	s_nop 0
	global_load_lds_dwordx4 v182, s[98:99]
	s_mov_b32 m0, s61
	s_nop 0
	global_load_lds_dwordx4 v186, s[98:99]
	s_waitcnt vmcnt(8)
	s_waitcnt lgkmcnt(0)
	s_barrier
	s_setprio 1
	s_waitcnt lgkmcnt(0)
	v_mfma_f32_16x16x32_bf16 v[62:65], v[66:69], v[162:165], v[62:65]
	v_mfma_f32_16x16x32_bf16 v[54:57], v[86:89], v[162:165], v[54:57]
	v_mfma_f32_16x16x32_bf16 v[46:49], v[66:69], v[170:173], v[46:49]
	v_mfma_f32_16x16x32_bf16 v[42:45], v[86:89], v[170:173], v[42:45]
	v_mfma_f32_16x16x32_bf16 v[30:33], v[66:69], v[196:199], v[30:33]
	v_mfma_f32_16x16x32_bf16 v[26:29], v[86:89], v[196:199], v[26:29]
	v_mfma_f32_16x16x32_bf16 v[14:17], v[66:69], v[204:207], v[14:17]
	v_mfma_f32_16x16x32_bf16 v[10:13], v[86:89], v[204:207], v[10:13]
	v_mfma_f32_16x16x32_bf16 v[62:65], v[70:73], v[166:169], v[62:65]
	v_mfma_f32_16x16x32_bf16 v[54:57], v[106:109], v[166:169], v[54:57]
	v_mfma_f32_16x16x32_bf16 v[46:49], v[70:73], v[174:177], v[46:49]
	v_mfma_f32_16x16x32_bf16 v[42:45], v[106:109], v[174:177], v[42:45]
	v_mfma_f32_16x16x32_bf16 v[30:33], v[70:73], v[200:203], v[30:33]
	v_mfma_f32_16x16x32_bf16 v[26:29], v[106:109], v[200:203], v[26:29]
	v_mfma_f32_16x16x32_bf16 v[14:17], v[70:73], v[208:211], v[14:17]
	v_mfma_f32_16x16x32_bf16 v[10:13], v[106:109], v[208:211], v[10:13]
	s_setprio 0
	s_setprio 1
	v_mfma_f32_16x16x32_bf16 v[58:61], v[146:149], v[162:165], v[58:61]
	v_mfma_f32_16x16x32_bf16 v[50:53], v[154:157], v[162:165], v[50:53]
	v_mfma_f32_16x16x32_bf16 v[38:41], v[146:149], v[170:173], v[38:41]
	v_mfma_f32_16x16x32_bf16 v[34:37], v[154:157], v[170:173], v[34:37]
	v_mfma_f32_16x16x32_bf16 v[22:25], v[146:149], v[196:199], v[22:25]
	v_mfma_f32_16x16x32_bf16 v[18:21], v[154:157], v[196:199], v[18:21]
	v_mfma_f32_16x16x32_bf16 v[6:9], v[146:149], v[204:207], v[6:9]
	v_mfma_f32_16x16x32_bf16 v[2:5], v[154:157], v[204:207], v[2:5]
	v_mfma_f32_16x16x32_bf16 v[58:61], v[150:153], v[166:169], v[58:61]
	v_mfma_f32_16x16x32_bf16 v[50:53], v[158:161], v[166:169], v[50:53]
	v_mfma_f32_16x16x32_bf16 v[38:41], v[150:153], v[174:177], v[38:41]
	v_mfma_f32_16x16x32_bf16 v[34:37], v[158:161], v[174:177], v[34:37]
	v_mfma_f32_16x16x32_bf16 v[22:25], v[150:153], v[200:203], v[22:25]
	v_mfma_f32_16x16x32_bf16 v[18:21], v[158:161], v[200:203], v[18:21]
	v_mfma_f32_16x16x32_bf16 v[6:9], v[150:153], v[208:211], v[6:9]
	v_mfma_f32_16x16x32_bf16 v[2:5], v[158:161], v[208:211], v[2:5]
	s_setprio 0
	s_barrier
	s_add_i32 s22, s22, 2
	s_add_u32 s8, s8, 0x100
	s_addc_u32 s9, s9, 0
	s_add_u32 s5, s5, 0x100
	s_addc_u32 s7, s7, 0
	s_cmp_gt_u32 s22, 13
	s_cbranch_scc0 .LBB0_991
	s_and_b64 vcc, exec, s[30:31]
	s_cbranch_vccz .LBB0_994

.Ls4_nocp:
.LBB0_1012:
	v_lshl_or_b32 v224, s0, 7, v214
	v_and_b32_e32 v197, 64, v181
	v_add_u32_e32 v197, 64, v197
	s_nop 0
	v_ashrrev_i32_e32 v225, 31, v224
	s_waitcnt lgkmcnt(0)
	s_waitcnt lgkmcnt(0)
	v_mov_b32_e32 v176, v174
	s_nop 0
	v_pk_mul_f32 v[142:143], v[142:143], v[176:177] op_sel_hi:[1,0]
	s_nop 0
	v_mul_f32_e32 v175, 0xbfb8aa3b, v142
	v_mul_f32_e32 v177, 0xbfb8aa3b, v143
	v_exp_f32_e32 v175, v175
	v_exp_f32_e32 v177, v177
	v_add_f32_e32 v175, 1.0, v175
	v_add_f32_e32 v177, 1.0, v177
	v_rcp_f32_e32 v226, v175
	v_rcp_f32_e32 v227, v177
	v_pk_mul_f32 v[144:145], v[144:145], v[176:177] op_sel_hi:[1,0]
	v_pk_mul_f32 v[138:139], v[138:139], v[176:177] op_sel_hi:[1,0]
	v_mul_f32_e32 v175, 0xbfb8aa3b, v144
	v_pk_mul_f32 v[142:143], v[142:143], v[226:227]
	v_exp_f32_e32 v175, v175
	v_pk_mul_f32 v[138:139], v[138:139], v[142:143]
	v_mul_f32_e32 v142, 0xbfb8aa3b, v145
	v_exp_f32_e32 v143, v142
	v_pk_mul_f32 v[134:135], v[134:135], v[176:177] op_sel_hi:[1,0]
	v_add_f32_e32 v142, 1.0, v175
	v_mul_f32_e32 v175, 0xbfb8aa3b, v134
	v_pk_mul_f32 v[140:141], v[140:141], v[176:177] op_sel_hi:[1,0]
	v_add_f32_e32 v143, 1.0, v143
	v_exp_f32_e32 v175, v175
	v_mul_f32_e32 v177, 0xbfb8aa3b, v135
	v_rcp_f32_e32 v142, v142
	v_exp_f32_e32 v177, v177
	v_rcp_f32_e32 v143, v143
	v_add_f32_e32 v175, 1.0, v175
	v_rcp_f32_e32 v226, v175
	v_add_f32_e32 v175, 1.0, v177
	v_pk_mul_f32 v[142:143], v[144:145], v[142:143]
	v_pk_mul_f32 v[136:137], v[136:137], v[176:177] op_sel_hi:[1,0]
	v_rcp_f32_e32 v227, v175
	v_pk_mul_f32 v[140:141], v[140:141], v[142:143]
	v_mul_f32_e32 v142, 0xbfb8aa3b, v136
	v_mul_f32_e32 v143, 0xbfb8aa3b, v137
	v_exp_f32_e32 v142, v142
	v_exp_f32_e32 v143, v143
	v_pk_mul_f32 v[130:131], v[130:131], v[176:177] op_sel_hi:[1,0]
	v_pk_mul_f32 v[134:135], v[134:135], v[226:227]
	v_pk_mul_f32 v[132:133], v[132:133], v[176:177] op_sel_hi:[1,0]
	v_pk_mul_f32 v[130:131], v[130:131], v[134:135]
	v_add_f32_e32 v134, 1.0, v142
	v_add_f32_e32 v135, 1.0, v143
	v_rcp_f32_e32 v134, v134
	v_rcp_f32_e32 v135, v135
	s_nop 0
	v_pk_mul_f32 v[134:135], v[136:137], v[134:135]
	s_nop 0
	v_pk_mul_f32 v[132:133], v[132:133], v[134:135]
	v_cvt_pk_bf16_f32 v134, v138, v139
	s_waitcnt lgkmcnt(0)
	v_cvt_pk_bf16_f32 v136, v130, v131
	v_cvt_pk_bf16_f32 v137, v132, v133
	v_mov_b64_e32 v[132:133], s[26:27]
	v_cvt_pk_bf16_f32 v135, v140, v141
	s_waitcnt lgkmcnt(0)
	v_mov_b32_e32 v138, v170
	v_mad_i64_i32 v[140:141], s[4:5], v210, s68, v[132:133]
	v_lshlrev_b64 v[130:131], 1, v[224:225]
	v_pk_mul_f32 v[126:127], v[126:127], v[138:139] op_sel_hi:[1,0]
	v_lshl_add_u64 v[140:141], v[140:141], 0, v[130:131]
	v_mul_f32_e32 v139, 0xbfb8aa3b, v126
	v_exp_f32_e32 v139, v139
	global_store_dwordx4 v[140:141], v[134:137], off
	v_pk_mul_f32 v[128:129], v[128:129], v[138:139] op_sel_hi:[1,0]
	s_nop 0
	v_mul_f32_e32 v134, 0xbfb8aa3b, v127
	v_exp_f32_e32 v135, v134
	v_mul_f32_e32 v136, 0xbfb8aa3b, v128
	v_mul_f32_e32 v137, 0xbfb8aa3b, v129
	v_exp_f32_e32 v136, v136
	v_exp_f32_e32 v137, v137
	v_add_f32_e32 v134, 1.0, v139
	v_add_f32_e32 v135, 1.0, v135
	v_rcp_f32_e32 v134, v134
	v_rcp_f32_e32 v135, v135
	v_add_f32_e32 v136, 1.0, v136
	v_add_f32_e32 v137, 1.0, v137
	v_rcp_f32_e32 v136, v136
	v_rcp_f32_e32 v137, v137
	v_pk_mul_f32 v[118:119], v[118:119], v[138:139] op_sel_hi:[1,0]
	v_pk_mul_f32 v[126:127], v[126:127], v[134:135]
	v_pk_mul_f32 v[120:121], v[120:121], v[138:139] op_sel_hi:[1,0]
	v_pk_mul_f32 v[118:119], v[118:119], v[126:127]
	v_pk_mul_f32 v[126:127], v[128:129], v[136:137]
	v_pk_mul_f32 v[122:123], v[122:123], v[138:139] op_sel_hi:[1,0]
	v_pk_mul_f32 v[120:121], v[120:121], v[126:127]
	v_mul_f32_e32 v128, 0xbfb8aa3b, v122
	v_mul_f32_e32 v126, 0xbfb8aa3b, v123
	v_exp_f32_e32 v128, v128
	v_exp_f32_e32 v127, v126
	v_pk_mul_f32 v[124:125], v[124:125], v[138:139] op_sel_hi:[1,0]
	v_pk_mul_f32 v[114:115], v[114:115], v[138:139] op_sel_hi:[1,0]
	v_add_f32_e32 v126, 1.0, v128
	v_add_f32_e32 v127, 1.0, v127
	v_mul_f32_e32 v128, 0xbfb8aa3b, v124
	v_mul_f32_e32 v129, 0xbfb8aa3b, v125
	v_rcp_f32_e32 v126, v126
	v_rcp_f32_e32 v127, v127
	v_exp_f32_e32 v128, v128
	v_exp_f32_e32 v129, v129
	v_pk_mul_f32 v[122:123], v[122:123], v[126:127]
	v_add_f32_e32 v126, 1.0, v128
	v_add_f32_e32 v127, 1.0, v129
	v_rcp_f32_e32 v126, v126
	v_rcp_f32_e32 v127, v127
	v_pk_mul_f32 v[122:123], v[114:115], v[122:123]
	v_pk_mul_f32 v[114:115], v[116:117], v[138:139] op_sel_hi:[1,0]
	v_pk_mul_f32 v[116:117], v[124:125], v[126:127]
	s_waitcnt lgkmcnt(0)
	v_pk_mul_f32 v[124:125], v[114:115], v[116:117]
	v_cvt_pk_bf16_f32 v114, v118, v119
	v_cvt_pk_bf16_f32 v115, v120, v121
	v_mad_i64_i32 v[120:121], s[4:5], v208, s68, v[132:133]
	s_waitcnt lgkmcnt(0)
	v_mov_b32_e32 v118, v166
	v_cvt_pk_bf16_f32 v116, v122, v123
	v_cvt_pk_bf16_f32 v117, v124, v125
	v_lshl_add_u64 v[120:121], v[120:121], 0, v[130:131]
	v_pk_mul_f32 v[110:111], v[110:111], v[118:119] op_sel_hi:[1,0]
	global_store_dwordx4 v[120:121], v[114:117], off
	v_mul_f32_e32 v119, 0xbfb8aa3b, v110
	v_exp_f32_e32 v119, v119
	v_mul_f32_e32 v114, 0xbfb8aa3b, v111
	v_exp_f32_e32 v115, v114
	v_pk_mul_f32 v[112:113], v[112:113], v[118:119] op_sel_hi:[1,0]
	s_nop 0
	v_mul_f32_e32 v116, 0xbfb8aa3b, v112
	v_mul_f32_e32 v117, 0xbfb8aa3b, v113
	v_exp_f32_e32 v116, v116
	v_exp_f32_e32 v117, v117
	v_add_f32_e32 v114, 1.0, v119
	v_add_f32_e32 v115, 1.0, v115
	v_rcp_f32_e32 v114, v114
	v_rcp_f32_e32 v115, v115
	v_add_f32_e32 v116, 1.0, v116
	v_add_f32_e32 v117, 1.0, v117
	v_rcp_f32_e32 v116, v116
	v_rcp_f32_e32 v117, v117
	v_pk_mul_f32 v[98:99], v[98:99], v[118:119] op_sel_hi:[1,0]
	v_pk_mul_f32 v[110:111], v[110:111], v[114:115]
	v_pk_mul_f32 v[100:101], v[100:101], v[118:119] op_sel_hi:[1,0]
	v_pk_mul_f32 v[98:99], v[98:99], v[110:111]
	v_pk_mul_f32 v[110:111], v[112:113], v[116:117]
	v_pk_mul_f32 v[102:103], v[102:103], v[118:119] op_sel_hi:[1,0]
	v_pk_mul_f32 v[100:101], v[100:101], v[110:111]
	v_mul_f32_e32 v112, 0xbfb8aa3b, v102
	v_mul_f32_e32 v110, 0xbfb8aa3b, v103
	v_exp_f32_e32 v112, v112
	v_exp_f32_e32 v111, v110
	v_pk_mul_f32 v[104:105], v[104:105], v[118:119] op_sel_hi:[1,0]
	v_pk_mul_f32 v[94:95], v[94:95], v[118:119] op_sel_hi:[1,0]
	v_add_f32_e32 v110, 1.0, v112
	v_add_f32_e32 v111, 1.0, v111
	v_mul_f32_e32 v112, 0xbfb8aa3b, v104
	v_mul_f32_e32 v113, 0xbfb8aa3b, v105
	v_rcp_f32_e32 v110, v110
	v_rcp_f32_e32 v111, v111
	v_exp_f32_e32 v112, v112
	v_exp_f32_e32 v113, v113
	v_pk_mul_f32 v[102:103], v[102:103], v[110:111]
	v_add_f32_e32 v110, 1.0, v112
	v_add_f32_e32 v111, 1.0, v113
	v_rcp_f32_e32 v110, v110
	v_rcp_f32_e32 v111, v111
	v_pk_mul_f32 v[102:103], v[94:95], v[102:103]
	v_pk_mul_f32 v[94:95], v[96:97], v[118:119] op_sel_hi:[1,0]
	v_pk_mul_f32 v[96:97], v[104:105], v[110:111]
	s_waitcnt lgkmcnt(0)
	v_pk_mul_f32 v[104:105], v[94:95], v[96:97]
	v_cvt_pk_bf16_f32 v94, v98, v99
	v_cvt_pk_bf16_f32 v95, v100, v101
	v_mad_i64_i32 v[100:101], s[4:5], v206, s68, v[132:133]
	s_waitcnt lgkmcnt(0)
	v_mov_b32_e32 v98, v162
	v_cvt_pk_bf16_f32 v96, v102, v103
	v_cvt_pk_bf16_f32 v97, v104, v105
	v_lshl_add_u64 v[100:101], v[100:101], 0, v[130:131]
	v_pk_mul_f32 v[90:91], v[90:91], v[98:99] op_sel_hi:[1,0]
	global_store_dwordx4 v[100:101], v[94:97], off
	v_mul_f32_e32 v99, 0xbfb8aa3b, v90
	v_exp_f32_e32 v99, v99
	v_mul_f32_e32 v94, 0xbfb8aa3b, v91
	v_exp_f32_e32 v95, v94
	v_pk_mul_f32 v[92:93], v[92:93], v[98:99] op_sel_hi:[1,0]
	s_nop 0
	v_mul_f32_e32 v96, 0xbfb8aa3b, v92
	v_mul_f32_e32 v97, 0xbfb8aa3b, v93
	v_exp_f32_e32 v96, v96
	v_exp_f32_e32 v97, v97
	v_add_f32_e32 v94, 1.0, v99
	v_add_f32_e32 v95, 1.0, v95
	v_rcp_f32_e32 v94, v94
	v_rcp_f32_e32 v95, v95
	v_add_f32_e32 v96, 1.0, v96
	v_add_f32_e32 v97, 1.0, v97
	v_rcp_f32_e32 v96, v96
	v_rcp_f32_e32 v97, v97
	v_pk_mul_f32 v[78:79], v[78:79], v[98:99] op_sel_hi:[1,0]
	v_pk_mul_f32 v[90:91], v[90:91], v[94:95]
	v_pk_mul_f32 v[82:83], v[82:83], v[98:99] op_sel_hi:[1,0]
	v_pk_mul_f32 v[78:79], v[78:79], v[90:91]
	v_pk_mul_f32 v[90:91], v[92:93], v[96:97]
	v_mul_f32_e32 v92, 0xbfb8aa3b, v82
	v_exp_f32_e32 v92, v92
	v_pk_mul_f32 v[80:81], v[80:81], v[98:99] op_sel_hi:[1,0]
	v_pk_mul_f32 v[84:85], v[84:85], v[98:99] op_sel_hi:[1,0]
	v_pk_mul_f32 v[80:81], v[80:81], v[90:91]
	v_mul_f32_e32 v90, 0xbfb8aa3b, v83
	v_exp_f32_e32 v91, v90
	v_add_f32_e32 v90, 1.0, v92
	v_mul_f32_e32 v92, 0xbfb8aa3b, v84
	v_mul_f32_e32 v93, 0xbfb8aa3b, v85
	v_exp_f32_e32 v92, v92
	v_exp_f32_e32 v93, v93
	v_add_f32_e32 v91, 1.0, v91
	v_rcp_f32_e32 v90, v90
	v_rcp_f32_e32 v91, v91
	v_add_f32_e32 v92, 1.0, v92
	v_add_f32_e32 v93, 1.0, v93
	v_rcp_f32_e32 v92, v92
	v_rcp_f32_e32 v93, v93
	v_pk_mul_f32 v[74:75], v[74:75], v[98:99] op_sel_hi:[1,0]
	v_pk_mul_f32 v[82:83], v[82:83], v[90:91]
	s_nop 0
	v_pk_mul_f32 v[82:83], v[74:75], v[82:83]
	v_pk_mul_f32 v[74:75], v[76:77], v[98:99] op_sel_hi:[1,0]
	v_pk_mul_f32 v[76:77], v[84:85], v[92:93]
	s_nop 0
	v_pk_mul_f32 v[84:85], v[74:75], v[76:77]
	v_cvt_pk_bf16_f32 v74, v78, v79
	v_mad_i64_i32 v[78:79], s[4:5], v204, s68, v[132:133]
	v_cvt_pk_bf16_f32 v75, v80, v81
	v_cvt_pk_bf16_f32 v76, v82, v83
	v_cvt_pk_bf16_f32 v77, v84, v85
	v_lshl_add_u64 v[78:79], v[78:79], 0, v[130:131]
	global_store_dwordx4 v[78:79], v[74:77], off
	s_mov_b64 s[100:101], s[6:7]
	s_andn2_b64 vcc, exec, s[6:7]
	s_cbranch_vccnz .LBB0_1030

.LBB0_1037:
	s_or_b64 exec, exec, s[6:7]
	s_andn2_b64 vcc, exec, s[100:101]
	s_cbranch_vccnz .Lcpe4_skip
	s_waitcnt vmcnt(8)
	global_store_dwordx4 v[248:249], v[146:149], off nt
	global_store_dwordx4 v[250:251], v[154:157], off nt
	global_store_dwordx4 v[252:253], v[150:153], off nt
	global_store_dwordx4 v[254:255], v[158:161], off nt
.Lcpe4_skip:
	s_cmp_eq_u32 s72, 10
	s_mov_b64 s[2:3], -1
	s_cbranch_scc1 .LBB0_987
	s_andn2_b64 vcc, exec, s[24:25]
	s_cbranch_vccnz .LBB0_986
	s_barrier
	s_branch .LBB0_986

.LBB0_1108:
	ds_read_b128 v[142:145], v150
	ds_read_b128 v[156:159], v150 offset:1024
	ds_read_b128 v[160:163], v150 offset:2048
	ds_read_b128 v[164:167], v150 offset:3072
	ds_read_b128 v[168:171], v151
	ds_read_b128 v[172:175], v151 offset:1024
	ds_read_b128 v[180:183], v151 offset:2048
	ds_read_b128 v[184:187], v151 offset:3072
	s_add_u32 s24, s22, 0xfff50080
	s_addc_u32 s25, s23, -1
	s_cmp_eq_u32 s51, 40
	s_cselect_b32 s27, s21, s25
	s_cselect_b32 s26, s20, s24
	s_cselect_b32 s25, s19, s50
	s_cselect_b32 s24, s18, s49
	s_mov_b32 m0, s36
	ds_read_b128 v[188:191], v152
	ds_read_b128 v[192:195], v152 offset:1024
	ds_read_b128 v[196:199], v152 offset:2048
	ds_read_b128 v[200:203], v152 offset:3072
	ds_read_b128 v[204:207], v152 offset:4096
	ds_read_b128 v[208:211], v152 offset:5120
	ds_read_b128 v[212:215], v152 offset:6144
	ds_read_b128 v[216:219], v152 offset:7168
	global_load_lds_dwordx4 v138, s[22:23]
	s_mov_b32 m0, s37
	s_nop 0
	global_load_lds_dwordx4 v140, s[22:23]
	s_waitcnt vmcnt(8)
	s_waitcnt lgkmcnt(0)
	s_barrier
	s_setprio 1
	s_waitcnt lgkmcnt(0)
	v_mfma_f32_16x16x32_bf16 v[126:129], v[142:145], v[188:191], v[126:129]
	v_mfma_f32_16x16x32_bf16 v[122:125], v[160:163], v[188:191], v[122:125]
	v_mfma_f32_16x16x32_bf16 v[110:113], v[142:145], v[196:199], v[110:113]
	v_mfma_f32_16x16x32_bf16 v[106:109], v[160:163], v[196:199], v[106:109]
	v_mfma_f32_16x16x32_bf16 v[94:97], v[142:145], v[204:207], v[94:97]
	v_mfma_f32_16x16x32_bf16 v[90:93], v[160:163], v[204:207], v[90:93]
	v_mfma_f32_16x16x32_bf16 v[78:81], v[142:145], v[212:215], v[78:81]
	v_mfma_f32_16x16x32_bf16 v[74:77], v[160:163], v[212:215], v[74:77]
	v_mfma_f32_16x16x32_bf16 v[126:129], v[156:159], v[192:195], v[126:129]
	v_mfma_f32_16x16x32_bf16 v[122:125], v[164:167], v[192:195], v[122:125]
	v_mfma_f32_16x16x32_bf16 v[110:113], v[156:159], v[200:203], v[110:113]
	v_mfma_f32_16x16x32_bf16 v[106:109], v[164:167], v[200:203], v[106:109]
	v_mfma_f32_16x16x32_bf16 v[94:97], v[156:159], v[208:211], v[94:97]
	v_mfma_f32_16x16x32_bf16 v[90:93], v[164:167], v[208:211], v[90:93]
	v_mfma_f32_16x16x32_bf16 v[78:81], v[156:159], v[216:219], v[78:81]
	v_mfma_f32_16x16x32_bf16 v[74:77], v[164:167], v[216:219], v[74:77]
	s_setprio 0
	s_setprio 1
	v_mfma_f32_16x16x32_bf16 v[118:121], v[168:171], v[188:191], v[118:121]
	v_mfma_f32_16x16x32_bf16 v[114:117], v[180:183], v[188:191], v[114:117]
	v_mfma_f32_16x16x32_bf16 v[102:105], v[168:171], v[196:199], v[102:105]
	v_mfma_f32_16x16x32_bf16 v[98:101], v[180:183], v[196:199], v[98:101]
	v_mfma_f32_16x16x32_bf16 v[86:89], v[168:171], v[204:207], v[86:89]
	v_mfma_f32_16x16x32_bf16 v[82:85], v[180:183], v[204:207], v[82:85]
	v_mfma_f32_16x16x32_bf16 v[70:73], v[168:171], v[212:215], v[70:73]
	v_mfma_f32_16x16x32_bf16 v[66:69], v[180:183], v[212:215], v[66:69]
	v_mfma_f32_16x16x32_bf16 v[118:121], v[172:175], v[192:195], v[118:121]
	v_mfma_f32_16x16x32_bf16 v[114:117], v[184:187], v[192:195], v[114:117]
	v_mfma_f32_16x16x32_bf16 v[102:105], v[172:175], v[200:203], v[102:105]
	v_mfma_f32_16x16x32_bf16 v[98:101], v[184:187], v[200:203], v[98:101]
	v_mfma_f32_16x16x32_bf16 v[86:89], v[172:175], v[208:211], v[86:89]
	v_mfma_f32_16x16x32_bf16 v[82:85], v[184:187], v[208:211], v[82:85]
	v_mfma_f32_16x16x32_bf16 v[70:73], v[172:175], v[216:219], v[70:73]
	v_mfma_f32_16x16x32_bf16 v[66:69], v[184:187], v[216:219], v[66:69]
	s_setprio 0
	s_barrier
	s_mov_b32 m0, s38
	s_add_u32 s52, s24, 0xb0000
	ds_read_b128 v[188:191], v152 offset:16384
	ds_read_b128 v[192:195], v152 offset:17408
	ds_read_b128 v[196:199], v152 offset:18432
	ds_read_b128 v[200:203], v152 offset:19456
	ds_read_b128 v[204:207], v152 offset:20480
	ds_read_b128 v[208:211], v152 offset:21504
	ds_read_b128 v[212:215], v152 offset:22528
	ds_read_b128 v[216:219], v152 offset:23552
	global_load_lds_dwordx4 v134, s[24:25]
	s_mov_b32 m0, s39
	s_addc_u32 s53, s25, 0
	global_load_lds_dwordx4 v130, s[24:25]
	s_mov_b32 m0, s40
	s_nop 0
	global_load_lds_dwordx4 v134, s[52:53]
	s_mov_b32 m0, s41
	s_nop 0
	global_load_lds_dwordx4 v130, s[52:53]
	s_mov_b32 m0, s4
	s_nop 0
	global_load_lds_dwordx4 v136, s[26:27]
	s_mov_b32 m0, s5
	s_nop 0
	global_load_lds_dwordx4 v132, s[26:27]
	s_waitcnt vmcnt(8)
	s_waitcnt lgkmcnt(0)
	s_barrier
	s_setprio 1
	s_waitcnt lgkmcnt(0)
	v_mfma_f32_16x16x32_bf16 v[62:65], v[142:145], v[188:191], v[62:65]
	v_mfma_f32_16x16x32_bf16 v[58:61], v[160:163], v[188:191], v[58:61]
	v_mfma_f32_16x16x32_bf16 v[46:49], v[142:145], v[196:199], v[46:49]
	v_mfma_f32_16x16x32_bf16 v[42:45], v[160:163], v[196:199], v[42:45]
	v_mfma_f32_16x16x32_bf16 v[34:37], v[142:145], v[204:207], v[34:37]
	v_mfma_f32_16x16x32_bf16 v[26:29], v[160:163], v[204:207], v[26:29]
	v_mfma_f32_16x16x32_bf16 v[18:21], v[142:145], v[212:215], v[18:21]
	v_mfma_f32_16x16x32_bf16 v[10:13], v[160:163], v[212:215], v[10:13]
	v_mfma_f32_16x16x32_bf16 v[62:65], v[156:159], v[192:195], v[62:65]
	v_mfma_f32_16x16x32_bf16 v[58:61], v[164:167], v[192:195], v[58:61]
	v_mfma_f32_16x16x32_bf16 v[46:49], v[156:159], v[200:203], v[46:49]
	v_mfma_f32_16x16x32_bf16 v[42:45], v[164:167], v[200:203], v[42:45]
	v_mfma_f32_16x16x32_bf16 v[34:37], v[156:159], v[208:211], v[34:37]
	v_mfma_f32_16x16x32_bf16 v[26:29], v[164:167], v[208:211], v[26:29]
	v_mfma_f32_16x16x32_bf16 v[18:21], v[156:159], v[216:219], v[18:21]
	v_mfma_f32_16x16x32_bf16 v[10:13], v[164:167], v[216:219], v[10:13]
	s_setprio 0
	s_setprio 1
	v_mfma_f32_16x16x32_bf16 v[54:57], v[168:171], v[188:191], v[54:57]
	v_mfma_f32_16x16x32_bf16 v[50:53], v[180:183], v[188:191], v[50:53]
	v_mfma_f32_16x16x32_bf16 v[38:41], v[168:171], v[196:199], v[38:41]
	v_mfma_f32_16x16x32_bf16 v[30:33], v[180:183], v[196:199], v[30:33]
	v_mfma_f32_16x16x32_bf16 v[22:25], v[168:171], v[204:207], v[22:25]
	v_mfma_f32_16x16x32_bf16 v[14:17], v[180:183], v[204:207], v[14:17]
	v_mfma_f32_16x16x32_bf16 v[6:9], v[168:171], v[212:215], v[6:9]
	v_mfma_f32_16x16x32_bf16 v[2:5], v[180:183], v[212:215], v[2:5]
	v_mfma_f32_16x16x32_bf16 v[54:57], v[172:175], v[192:195], v[54:57]
	v_mfma_f32_16x16x32_bf16 v[50:53], v[184:187], v[192:195], v[50:53]
	v_mfma_f32_16x16x32_bf16 v[38:41], v[172:175], v[200:203], v[38:41]
	v_mfma_f32_16x16x32_bf16 v[30:33], v[184:187], v[200:203], v[30:33]
	v_mfma_f32_16x16x32_bf16 v[22:25], v[172:175], v[208:211], v[22:25]
	v_mfma_f32_16x16x32_bf16 v[14:17], v[184:187], v[208:211], v[14:17]
	v_mfma_f32_16x16x32_bf16 v[6:9], v[172:175], v[216:219], v[6:9]
	v_mfma_f32_16x16x32_bf16 v[2:5], v[184:187], v[216:219], v[2:5]
	s_setprio 0
	s_barrier
	ds_read_b128 v[142:145], v153
	ds_read_b128 v[156:159], v153 offset:1024
	ds_read_b128 v[160:163], v153 offset:2048
	ds_read_b128 v[164:167], v153 offset:3072
	ds_read_b128 v[168:171], v154
	ds_read_b128 v[172:175], v154 offset:1024
	ds_read_b128 v[180:183], v154 offset:2048
	ds_read_b128 v[184:187], v154 offset:3072
	s_add_u32 s26, s26, 0xb0000
	s_addc_u32 s27, s27, 0
	s_mov_b32 m0, s29
	ds_read_b128 v[188:191], v152 offset:32768
	ds_read_b128 v[192:195], v152 offset:33792
	ds_read_b128 v[196:199], v152 offset:34816
	ds_read_b128 v[200:203], v152 offset:35840
	ds_read_b128 v[204:207], v152 offset:36864
	ds_read_b128 v[208:211], v152 offset:37888
	ds_read_b128 v[212:215], v152 offset:38912
	ds_read_b128 v[216:219], v152 offset:39936
	global_load_lds_dwordx4 v136, s[26:27]
	s_mov_b32 m0, s30
	s_nop 0
	global_load_lds_dwordx4 v132, s[26:27]
	s_waitcnt vmcnt(8)
	s_waitcnt lgkmcnt(0)
	s_barrier
	s_setprio 1
	s_waitcnt lgkmcnt(0)
	v_mfma_f32_16x16x32_bf16 v[126:129], v[142:145], v[188:191], v[126:129]
	v_mfma_f32_16x16x32_bf16 v[122:125], v[160:163], v[188:191], v[122:125]
	v_mfma_f32_16x16x32_bf16 v[110:113], v[142:145], v[196:199], v[110:113]
	v_mfma_f32_16x16x32_bf16 v[106:109], v[160:163], v[196:199], v[106:109]
	v_mfma_f32_16x16x32_bf16 v[94:97], v[142:145], v[204:207], v[94:97]
	v_mfma_f32_16x16x32_bf16 v[90:93], v[160:163], v[204:207], v[90:93]
	v_mfma_f32_16x16x32_bf16 v[78:81], v[142:145], v[212:215], v[78:81]
	v_mfma_f32_16x16x32_bf16 v[74:77], v[160:163], v[212:215], v[74:77]
	v_mfma_f32_16x16x32_bf16 v[126:129], v[156:159], v[192:195], v[126:129]
	v_mfma_f32_16x16x32_bf16 v[122:125], v[164:167], v[192:195], v[122:125]
	v_mfma_f32_16x16x32_bf16 v[110:113], v[156:159], v[200:203], v[110:113]
	v_mfma_f32_16x16x32_bf16 v[106:109], v[164:167], v[200:203], v[106:109]
	v_mfma_f32_16x16x32_bf16 v[94:97], v[156:159], v[208:211], v[94:97]
	v_mfma_f32_16x16x32_bf16 v[90:93], v[164:167], v[208:211], v[90:93]
	v_mfma_f32_16x16x32_bf16 v[78:81], v[156:159], v[216:219], v[78:81]
	v_mfma_f32_16x16x32_bf16 v[74:77], v[164:167], v[216:219], v[74:77]
	s_setprio 0
	s_setprio 1
	v_mfma_f32_16x16x32_bf16 v[118:121], v[168:171], v[188:191], v[118:121]
	v_mfma_f32_16x16x32_bf16 v[114:117], v[180:183], v[188:191], v[114:117]
	v_mfma_f32_16x16x32_bf16 v[102:105], v[168:171], v[196:199], v[102:105]
	v_mfma_f32_16x16x32_bf16 v[98:101], v[180:183], v[196:199], v[98:101]
	v_mfma_f32_16x16x32_bf16 v[86:89], v[168:171], v[204:207], v[86:89]
	v_mfma_f32_16x16x32_bf16 v[82:85], v[180:183], v[204:207], v[82:85]
	v_mfma_f32_16x16x32_bf16 v[70:73], v[168:171], v[212:215], v[70:73]
	v_mfma_f32_16x16x32_bf16 v[66:69], v[180:183], v[212:215], v[66:69]
	v_mfma_f32_16x16x32_bf16 v[118:121], v[172:175], v[192:195], v[118:121]
	v_mfma_f32_16x16x32_bf16 v[114:117], v[184:187], v[192:195], v[114:117]
	v_mfma_f32_16x16x32_bf16 v[102:105], v[172:175], v[200:203], v[102:105]
	v_mfma_f32_16x16x32_bf16 v[98:101], v[184:187], v[200:203], v[98:101]
	v_mfma_f32_16x16x32_bf16 v[86:89], v[172:175], v[208:211], v[86:89]
	v_mfma_f32_16x16x32_bf16 v[82:85], v[184:187], v[208:211], v[82:85]
	v_mfma_f32_16x16x32_bf16 v[70:73], v[172:175], v[216:219], v[70:73]
	v_mfma_f32_16x16x32_bf16 v[66:69], v[184:187], v[216:219], v[66:69]
	s_setprio 0
	s_barrier
	s_mov_b32 m0, s42
	ds_read_b128 v[188:191], v152 offset:49152
	ds_read_b128 v[192:195], v152 offset:50176
	ds_read_b128 v[196:199], v152 offset:51200
	ds_read_b128 v[200:203], v152 offset:52224
	ds_read_b128 v[204:207], v152 offset:53248
	ds_read_b128 v[208:211], v152 offset:54272
	ds_read_b128 v[212:215], v152 offset:55296
	ds_read_b128 v[216:219], v152 offset:56320
	s_add_u32 s98, s24, 0x80
	s_addc_u32 s99, s25, 0
	global_load_lds_dwordx4 v134, s[98:99]
	s_mov_b32 m0, s43
	s_add_u32 s24, s24, 0xb0080
	s_addc_u32 s25, s25, 0
	global_load_lds_dwordx4 v130, s[98:99]
	s_mov_b32 m0, s44
	s_nop 0
	global_load_lds_dwordx4 v134, s[24:25]
	s_mov_b32 m0, s45
	s_nop 0
	global_load_lds_dwordx4 v130, s[24:25]
	s_add_u32 s98, s26, 0xfff50080
	s_addc_u32 s99, s27, -1
	s_mov_b32 m0, s0
	s_nop 0
	global_load_lds_dwordx4 v136, s[98:99]
	s_mov_b32 m0, s1
	s_nop 0
	global_load_lds_dwordx4 v132, s[98:99]
	s_waitcnt vmcnt(8)
	s_waitcnt lgkmcnt(0)
	s_barrier
	s_setprio 1
	s_waitcnt lgkmcnt(0)
	v_mfma_f32_16x16x32_bf16 v[62:65], v[142:145], v[188:191], v[62:65]
	v_mfma_f32_16x16x32_bf16 v[58:61], v[160:163], v[188:191], v[58:61]
	v_mfma_f32_16x16x32_bf16 v[46:49], v[142:145], v[196:199], v[46:49]
	v_mfma_f32_16x16x32_bf16 v[42:45], v[160:163], v[196:199], v[42:45]
	v_mfma_f32_16x16x32_bf16 v[34:37], v[142:145], v[204:207], v[34:37]
	v_mfma_f32_16x16x32_bf16 v[26:29], v[160:163], v[204:207], v[26:29]
	v_mfma_f32_16x16x32_bf16 v[18:21], v[142:145], v[212:215], v[18:21]
	v_mfma_f32_16x16x32_bf16 v[10:13], v[160:163], v[212:215], v[10:13]
	v_mfma_f32_16x16x32_bf16 v[62:65], v[156:159], v[192:195], v[62:65]
	v_mfma_f32_16x16x32_bf16 v[58:61], v[164:167], v[192:195], v[58:61]
	v_mfma_f32_16x16x32_bf16 v[46:49], v[156:159], v[200:203], v[46:49]
	v_mfma_f32_16x16x32_bf16 v[42:45], v[164:167], v[200:203], v[42:45]
	v_mfma_f32_16x16x32_bf16 v[34:37], v[156:159], v[208:211], v[34:37]
	v_mfma_f32_16x16x32_bf16 v[26:29], v[164:167], v[208:211], v[26:29]
	v_mfma_f32_16x16x32_bf16 v[18:21], v[156:159], v[216:219], v[18:21]
	v_mfma_f32_16x16x32_bf16 v[10:13], v[164:167], v[216:219], v[10:13]
	s_setprio 0
	s_setprio 1
	v_mfma_f32_16x16x32_bf16 v[54:57], v[168:171], v[188:191], v[54:57]
	v_mfma_f32_16x16x32_bf16 v[50:53], v[180:183], v[188:191], v[50:53]
	v_mfma_f32_16x16x32_bf16 v[38:41], v[168:171], v[196:199], v[38:41]
	v_mfma_f32_16x16x32_bf16 v[30:33], v[180:183], v[196:199], v[30:33]
	v_mfma_f32_16x16x32_bf16 v[22:25], v[168:171], v[204:207], v[22:25]
	v_mfma_f32_16x16x32_bf16 v[14:17], v[180:183], v[204:207], v[14:17]
	v_mfma_f32_16x16x32_bf16 v[6:9], v[168:171], v[212:215], v[6:9]
	v_mfma_f32_16x16x32_bf16 v[2:5], v[180:183], v[212:215], v[2:5]
	v_mfma_f32_16x16x32_bf16 v[54:57], v[172:175], v[192:195], v[54:57]
	v_mfma_f32_16x16x32_bf16 v[50:53], v[184:187], v[192:195], v[50:53]
	v_mfma_f32_16x16x32_bf16 v[38:41], v[172:175], v[200:203], v[38:41]
	v_mfma_f32_16x16x32_bf16 v[30:33], v[184:187], v[200:203], v[30:33]
	v_mfma_f32_16x16x32_bf16 v[22:25], v[172:175], v[208:211], v[22:25]
	v_mfma_f32_16x16x32_bf16 v[14:17], v[184:187], v[208:211], v[14:17]
	v_mfma_f32_16x16x32_bf16 v[6:9], v[172:175], v[216:219], v[6:9]
	v_mfma_f32_16x16x32_bf16 v[2:5], v[184:187], v[216:219], v[2:5]
	s_setprio 0
	s_barrier
	s_add_i32 s51, s51, 2
	s_add_u32 s22, s22, 0x100
	s_addc_u32 s23, s23, 0
	s_add_u32 s49, s49, 0x100
	s_addc_u32 s50, s50, 0
	s_cmp_gt_u32 s51, 41
	s_cbranch_scc0 .LBB0_1108
	s_and_b64 vcc, exec, s[16:17]
	s_cbranch_vccz .LBB0_1111
	s_barrier
